# P7 XN2 stores sc1 (write-through) on top of v089
# speedup vs baseline: 1.0165x; 1.0165x over previous
.LBB0_807:
	s_ashr_i32 s7, s6, 31
	s_lshl_b64 s[0:1], s[6:7], 6
	s_waitcnt lgkmcnt(0)
	v_lshl_add_u64 v[16:17], v[24:25], 0, s[0:1]
	global_load_dwordx4 v[30:33], v[16:17], off
	s_add_i32 s12, s3, s6
	s_cmp_lt_i32 s12, 0x8000
	s_cselect_b32 s0, s12, s6
	s_ashr_i32 s1, s0, 31
	s_lshl_b64 s[20:21], s[0:1], 6
	s_lshl_b64 s[14:15], s[0:1], 11
	s_lshl_b64 s[0:1], s[0:1], 2
	s_add_u32 s16, s30, s0
	s_addc_u32 s17, s31, s1
	s_lshl_b64 s[0:1], s[6:7], 11
	v_lshl_add_u64 v[28:29], v[22:23], 0, s[0:1]
	global_load_dwordx2 v[34:35], v[28:29], off offset:1536 nt
	v_lshl_add_u64 v[16:17], v[26:27], 0, s[0:1]
	s_lshl_b64 s[0:1], s[6:7], 2
	s_add_u32 s0, s30, s0
	s_addc_u32 s1, s31, s1
	global_load_dwordx2 v[36:37], v[16:17], off offset:512 nt
	global_load_dwordx2 v[38:39], v[28:29], off offset:512 nt
	global_load_dwordx2 v[40:41], v[16:17], off offset:1024 nt
	global_load_dwordx2 v[42:43], v[28:29], off offset:1024 nt
	global_load_dwordx2 v[44:45], v[16:17], off offset:1536 nt
	global_load_dwordx2 v[46:47], v[28:29], off nt
	global_load_dwordx2 v[56:57], v[16:17], off nt
	global_load_dword v58, v21, s[0:1]
	v_lshl_add_u64 v[16:17], v[24:25], 0, s[20:21]
	global_load_dwordx4 v[16:19], v[16:17], off
	s_cmpk_gt_i32 s12, 0x7fff
	s_waitcnt vmcnt(10)
	v_mov_b32_e32 v60, v31
	v_mov_b32_e32 v61, v32
	v_mov_b32_e32 v31, v33
	v_pk_add_f32 v[30:31], v[60:61], v[30:31]
	s_waitcnt vmcnt(8)
	v_and_b32_e32 v61, 0xffff0000, v36
	v_add_f32_e32 v30, v30, v31
	ds_bpermute_b32 v32, v20, v30
	v_and_b32_e32 v55, 0xffff0000, v35
	v_lshlrev_b32_e32 v59, 16, v35
	s_waitcnt vmcnt(4)
	v_lshlrev_b32_e32 v70, 16, v44
	v_and_b32_e32 v72, 0xffff0000, v44
	s_waitcnt lgkmcnt(0)
	v_add_f32_e32 v30, v30, v32
	ds_bpermute_b32 v32, v48, v30
	v_lshlrev_b32_e32 v74, 16, v45
	v_and_b32_e32 v76, 0xffff0000, v45
	s_waitcnt vmcnt(2)
	v_lshlrev_b32_e32 v44, 16, v57
	v_and_b32_e32 v45, 0xffff0000, v57
	s_waitcnt lgkmcnt(0)
	v_add_f32_e32 v30, v30, v32
	v_fmamk_f32 v30, v30, 0x3a800000, v53
	v_mul_f32_e32 v32, 0x4f800000, v30
	v_cmp_gt_f32_e32 vcc, s19, v30
	s_waitcnt vmcnt(1)
	v_mul_f32_e32 v57, v58, v55
	v_and_b32_e32 v31, 0xffff0000, v34
	v_cndmask_b32_e32 v30, v30, v32, vcc
	v_sqrt_f32_e32 v32, v30
	v_lshlrev_b32_e32 v33, 16, v34
	v_lshlrev_b32_e32 v35, 16, v36
	v_lshlrev_b32_e32 v34, 16, v38
	v_add_u32_e32 v55, -1, v32
	v_and_b32_e32 v60, 0xffff0000, v38
	v_lshlrev_b32_e32 v62, 16, v39
	v_and_b32_e32 v36, 0xffff0000, v39
	v_lshlrev_b32_e32 v39, 16, v40
	v_lshlrev_b32_e32 v38, 16, v42
	v_and_b32_e32 v65, 0xffff0000, v40
	v_and_b32_e32 v64, 0xffff0000, v42
	v_lshlrev_b32_e32 v66, 16, v43
	v_and_b32_e32 v40, 0xffff0000, v43
	v_lshlrev_b32_e32 v42, 16, v47
	v_and_b32_e32 v43, 0xffff0000, v47
	v_lshlrev_b32_e32 v68, 16, v46
	v_and_b32_e32 v69, 0xffff0000, v46
	v_lshlrev_b32_e32 v46, 16, v56
	v_and_b32_e32 v47, 0xffff0000, v56
	v_mul_f32_e32 v71, v58, v59
	v_add_u32_e32 v56, 1, v32
	v_fma_f32 v59, -v55, v32, v30
	v_fma_f32 v73, -v56, v32, v30
	v_cmp_ge_f32_e64 s[0:1], 0, v59
	v_lshlrev_b32_e32 v63, 16, v37
	v_and_b32_e32 v37, 0xffff0000, v37
	v_cndmask_b32_e64 v32, v32, v55, s[0:1]
	v_cmp_lt_f32_e64 s[0:1], 0, v73
	v_lshlrev_b32_e32 v67, 16, v41
	v_and_b32_e32 v41, 0xffff0000, v41
	v_cndmask_b32_e64 v32, v32, v56, s[0:1]
	v_mul_f32_e32 v55, 0x37800000, v32
	v_cndmask_b32_e32 v32, v32, v55, vcc
	v_cmp_class_f32_e32 vcc, v30, v54
	v_mov_b32_e32 v73, v58
	s_waitcnt vmcnt(0)
	v_add_f32_e32 v16, v16, v17
	v_cndmask_b32_e32 v30, v32, v30, vcc
	v_div_scale_f32 v32, s[0:1], v30, v30, 1.0
	v_rcp_f32_e32 v55, v32
	v_div_scale_f32 v56, vcc, 1.0, v30, 1.0
	v_add_f32_e32 v18, v18, v19
	v_fma_f32 v59, -v32, v55, 1.0
	v_fmac_f32_e32 v55, v59, v55
	v_mul_f32_e32 v59, v56, v55
	v_fma_f32 v75, -v32, v59, v56
	v_fmac_f32_e32 v59, v75, v55
	v_fma_f32 v32, -v32, v59, v56
	v_div_fmas_f32 v32, v32, v55, v59
	v_div_fixup_f32 v59, v32, v30, 1.0
	v_mov_b32_e32 v30, v59
	v_mul_f32_e32 v32, v59, v74
	v_pk_mul_f32 v[44:45], v[30:31], v[44:45] op_sel_hi:[0,1]
	v_pk_mul_f32 v[34:35], v[58:59], v[34:35]
	v_pk_mul_f32 v[60:61], v[58:59], v[60:61]
	v_pk_mul_f32 v[62:63], v[58:59], v[62:63]
	v_pk_mul_f32 v[36:37], v[58:59], v[36:37]
	v_pk_mul_f32 v[38:39], v[58:59], v[38:39]
	v_pk_mul_f32 v[64:65], v[58:59], v[64:65]
	v_pk_mul_f32 v[66:67], v[58:59], v[66:67]
	v_pk_mul_f32 v[40:41], v[58:59], v[40:41]
	v_mul_f32_e32 v75, v59, v70
	v_mul_f32_e32 v77, v59, v72
	v_mul_f32_e32 v55, v59, v76
	v_mul_f32_e32 v59, v2, v32
	v_pk_mul_f32 v[46:47], v[30:31], v[46:47] op_sel_hi:[0,1]
	v_pk_mul_f32 v[44:45], v[14:15], v[44:45]
	v_pk_mul_f32 v[46:47], v[12:13], v[46:47]
	v_pk_fma_f32 v[80:81], v[58:59], v[42:43], v[44:45] op_sel_hi:[0,1,1]
	v_pk_fma_f32 v[68:69], v[58:59], v[68:69], v[46:47] op_sel_hi:[0,1,1]
	v_pk_mov_b32 v[42:43], v[80:81], v[0:1] op_sel:[1,0]
	v_mov_b32_e32 v74, v81
	v_pk_mul_f32 v[42:43], v[42:43], v[74:75]
	v_pk_mov_b32 v[82:83], v[68:69], v[0:1] op_sel:[1,0]
	v_mov_b32_e32 v74, v69
	v_mov_b32_e32 v72, v80
	v_mov_b32_e32 v32, v80
	v_mov_b32_e32 v44, v68
	v_mov_b32_e32 v45, v58
	v_mov_b32_e32 v46, v68
	v_mov_b32_e32 v47, v33
	v_pk_mul_f32 v[74:75], v[82:83], v[74:75]
	v_pk_fma_f32 v[32:33], v[72:73], v[32:33], v[42:43]
	v_pk_fma_f32 v[72:73], v[44:45], v[46:47], v[74:75]
	v_mul_f32_e32 v79, v3, v55
	v_pk_add_f32 v[42:43], v[72:73], v[32:33]
	v_pk_mul_f32 v[32:33], v[72:73], v[32:33]
	v_add_f32_e32 v16, v16, v18
	v_mov_b32_e32 v43, v33
	v_mov_b32_e32 v32, v63
	v_mov_b32_e32 v33, v37
	v_mov_b32_e32 v63, v36
	v_mov_b32_e32 v36, v35
	v_mov_b32_e32 v37, v61
	v_mov_b32_e32 v35, v60
	v_pk_fma_f32 v[60:61], v[8:9], v[36:37], v[34:35]
	v_pk_fma_f32 v[62:63], v[10:11], v[32:33], v[62:63]
	v_mov_b32_e32 v36, v61
	v_mov_b32_e32 v37, v1
	v_mov_b32_e32 v76, v61
	v_mov_b32_e32 v32, v63
	v_mov_b32_e32 v33, v1
	v_mov_b32_e32 v34, v60
	v_mov_b32_e32 v35, v58
	v_mov_b32_e32 v30, v60
	v_pk_mul_f32 v[36:37], v[36:37], v[76:77]
	v_mov_b32_e32 v76, v63
	v_pk_fma_f32 v[74:75], v[34:35], v[30:31], v[36:37]
	v_mov_b32_e32 v34, v62
	v_mov_b32_e32 v30, v62
	v_pk_mul_f32 v[32:33], v[32:33], v[76:77]
	ds_bpermute_b32 v18, v20, v16
	v_pk_fma_f32 v[30:31], v[34:35], v[30:31], v[32:33]
	s_waitcnt lgkmcnt(0)
	v_add_f32_e32 v16, v16, v18
	v_pk_add_f32 v[32:33], v[74:75], v[30:31]
	v_pk_mul_f32 v[30:31], v[74:75], v[30:31]
	v_mov_b32_e32 v74, v73
	v_mov_b32_e32 v33, v31
	v_pk_add_f32 v[30:31], v[42:43], v[32:33]
	v_mov_b32_e32 v32, v67
	v_mov_b32_e32 v33, v41
	v_mov_b32_e32 v67, v40
	v_pk_fma_f32 v[66:67], v[6:7], v[32:33], v[66:67]
	s_nop 0
	v_mov_b32_e32 v78, v66
	v_mov_b32_e32 v56, v66
	v_pk_add_f32 v[56:57], v[78:79], v[56:57]
	v_mul_f32_e32 v32, v67, v67
	v_pk_fma_f32 v[32:33], v[66:67], v[66:67], v[32:33] op_sel_hi:[1,1,0]
	v_pk_mul_f32 v[34:35], v[56:57], v[56:57]
	s_nop 0
	v_mov_b32_e32 v33, v35
	v_mov_b32_e32 v34, v39
	v_mov_b32_e32 v35, v65
	v_mov_b32_e32 v39, v64
	v_pk_fma_f32 v[64:65], v[4:5], v[34:35], v[38:39]
	s_nop 0
	v_mov_b32_e32 v58, v64
	v_mov_b32_e32 v70, v64
	v_pk_add_f32 v[58:59], v[58:59], v[70:71]
	v_mul_f32_e32 v34, v65, v65
	v_pk_fma_f32 v[34:35], v[64:65], v[64:65], v[34:35] op_sel_hi:[1,1,0]
	v_pk_mul_f32 v[36:37], v[58:59], v[58:59]
	v_lshl_add_u64 v[70:71], v[26:27], 0, s[14:15]
	v_mov_b32_e32 v35, v37
	v_pk_add_f32 v[32:33], v[34:35], v[32:33]
	v_lshl_add_u64 v[34:35], v[22:23], 0, s[14:15]
	v_pk_add_f32 v[30:31], v[30:31], v[32:33]
	s_nop 0
	v_add_f32_e32 v31, v30, v31
	ds_bpermute_b32 v32, v20, v31
	global_load_dword v30, v21, s[16:17]
	s_waitcnt lgkmcnt(0)
	v_add_f32_e32 v31, v31, v32
	ds_bpermute_b32 v36, v48, v31
	global_load_dwordx2 v[32:33], v[34:35], off nt
	global_load_dwordx2 v[42:43], v[34:35], off offset:512 nt
	global_load_dwordx2 v[38:39], v[34:35], off offset:1024 nt
	global_load_dwordx2 v[46:47], v[34:35], off offset:1536 nt
	s_waitcnt lgkmcnt(0)
	v_add_f32_e32 v31, v31, v36
	global_load_dwordx2 v[34:35], v[70:71], off nt
	global_load_dwordx2 v[44:45], v[70:71], off offset:512 nt
	global_load_dwordx2 v[40:41], v[70:71], off offset:1024 nt
	global_load_dwordx2 v[36:37], v[70:71], off offset:1536 nt
	ds_bpermute_b32 v55, v49, v31
	s_waitcnt lgkmcnt(0)
	v_add_f32_e32 v31, v31, v55
	ds_bpermute_b32 v55, v50, v31
	s_waitcnt lgkmcnt(0)
	v_add_f32_e32 v31, v31, v55
	ds_bpermute_b32 v55, v51, v31
	s_waitcnt lgkmcnt(0)
	v_add_f32_e32 v31, v31, v55
	ds_bpermute_b32 v55, v52, v31
	s_waitcnt lgkmcnt(0)
	v_add_f32_e32 v17, v31, v55
	v_fmamk_f32 v17, v17, 0x3a800000, v53
	v_mul_f32_e32 v31, 0x4f800000, v17
	v_cmp_gt_f32_e32 vcc, s19, v17
	s_nop 1
	v_cndmask_b32_e32 v17, v17, v31, vcc
	v_sqrt_f32_e32 v31, v17
	s_nop 0
	v_add_u32_e32 v19, -1, v31
	v_fma_f32 v55, -v19, v31, v17
	v_cmp_ge_f32_e64 s[0:1], 0, v55
	v_add_u32_e32 v55, 1, v31
	s_nop 0
	v_cndmask_b32_e64 v19, v31, v19, s[0:1]
	v_fma_f32 v31, -v55, v31, v17
	v_cmp_lt_f32_e64 s[0:1], 0, v31
	s_nop 1
	v_cndmask_b32_e64 v19, v19, v55, s[0:1]
	v_mul_f32_e32 v31, 0x37800000, v19
	v_cndmask_b32_e32 v19, v19, v31, vcc
	v_cmp_class_f32_e32 vcc, v17, v54
	s_nop 1
	v_cndmask_b32_e32 v19, v19, v17, vcc
	v_div_scale_f32 v31, s[0:1], v19, v19, 1.0
	v_rcp_f32_e32 v55, v31
	ds_bpermute_b32 v17, v48, v16
	v_fma_f32 v18, -v31, v55, 1.0
	v_fmac_f32_e32 v55, v18, v55
	v_div_scale_f32 v18, vcc, 1.0, v19, 1.0
	v_mul_f32_e32 v56, v18, v55
	v_fma_f32 v58, -v31, v56, v18
	v_fmac_f32_e32 v56, v58, v55
	v_fma_f32 v18, -v31, v56, v18
	v_div_fmas_f32 v18, v18, v55, v56
	v_div_fixup_f32 v18, v18, v19, 1.0
	v_pk_mul_f32 v[60:61], v[18:19], v[60:61] op_sel_hi:[0,1]
	v_pk_mul_f32 v[62:63], v[18:19], v[62:63] op_sel_hi:[0,1]
	v_cvt_pk_bf16_f32 v60, v60, v61
	v_cvt_pk_bf16_f32 v61, v62, v63
	global_store_dwordx2 v[28:29], v[60:61], off offset:512 sc1
	v_pk_mul_f32 v[60:61], v[18:19], v[64:65] op_sel_hi:[0,1]
	v_pk_mul_f32 v[62:63], v[18:19], v[66:67] op_sel_hi:[0,1]
	v_cvt_pk_bf16_f32 v60, v60, v61
	v_cvt_pk_bf16_f32 v61, v62, v63
	v_mov_b32_e32 v56, v59
	v_pk_mul_f32 v[68:69], v[18:19], v[68:69] op_sel_hi:[0,1]
	v_pk_mul_f32 v[70:71], v[18:19], v[80:81] op_sel_hi:[0,1]
	global_store_dwordx2 v[28:29], v[60:61], off offset:1024 sc1
	v_pk_mul_f32 v[60:61], v[18:19], v[74:75] op_sel_hi:[0,1]
	v_pk_mul_f32 v[18:19], v[18:19], v[56:57] op_sel_hi:[0,1]
	v_cvt_pk_bf16_f32 v68, v68, v69
	v_cvt_pk_bf16_f32 v69, v70, v71
	v_cvt_pk_bf16_f32 v58, v60, v61
	v_cvt_pk_bf16_f32 v59, v18, v19
	global_store_dwordx2 v[28:29], v[68:69], off sc1
	global_store_dwordx2 v[28:29], v[58:59], off offset:1536 sc1
	s_cbranch_scc1 .LBB0_806
	s_waitcnt lgkmcnt(0)
	v_add_f32_e32 v16, v16, v17
	v_fmamk_f32 v16, v16, 0x3a800000, v53
	v_mul_f32_e32 v17, 0x4f800000, v16
	v_cmp_gt_f32_e32 vcc, s19, v16
	s_waitcnt vmcnt(8)
	v_lshlrev_b32_e32 v19, 16, v47
	s_waitcnt vmcnt(6)
	v_lshlrev_b32_e32 v57, 16, v44
	v_cndmask_b32_e32 v16, v16, v17, vcc
	v_sqrt_f32_e32 v18, v16
	v_and_b32_e32 v17, 0xffff0000, v47
	v_lshlrev_b32_e32 v47, 16, v46
	v_and_b32_e32 v59, 0xffff0000, v44
	v_add_u32_e32 v28, -1, v18
	v_fma_f32 v29, -v28, v18, v16
	v_cmp_ge_f32_e64 s[0:1], 0, v29
	v_add_u32_e32 v29, 1, v18
	v_lshlrev_b32_e32 v61, 16, v45
	v_cndmask_b32_e64 v28, v18, v28, s[0:1]
	v_fma_f32 v18, -v29, v18, v16
	v_cmp_lt_f32_e64 s[0:1], 0, v18
	v_and_b32_e32 v45, 0xffff0000, v45
	v_and_b32_e32 v44, 0xffff0000, v43
	v_cndmask_b32_e64 v18, v28, v29, s[0:1]
	v_mul_f32_e32 v28, 0x37800000, v18
	v_cndmask_b32_e32 v18, v18, v28, vcc
	v_cmp_class_f32_e32 vcc, v16, v54
	v_and_b32_e32 v29, 0xffff0000, v46
	v_lshlrev_b32_e32 v56, 16, v42
	v_cndmask_b32_e32 v16, v18, v16, vcc
	v_div_scale_f32 v18, s[0:1], v16, v16, 1.0
	v_rcp_f32_e32 v28, v18
	v_and_b32_e32 v58, 0xffff0000, v42
	v_lshlrev_b32_e32 v60, 16, v43
	s_waitcnt vmcnt(5)
	v_and_b32_e32 v63, 0xffff0000, v40
	v_fma_f32 v31, -v18, v28, 1.0
	v_fmac_f32_e32 v28, v31, v28
	v_div_scale_f32 v31, vcc, 1.0, v16, 1.0
	v_mul_f32_e32 v46, v31, v28
	v_fma_f32 v55, -v18, v46, v31
	v_fmac_f32_e32 v46, v55, v28
	v_fma_f32 v18, -v18, v46, v31
	v_div_fmas_f32 v18, v18, v28, v46
	v_div_fixup_f32 v31, v18, v16, 1.0
	v_pk_mul_f32 v[42:43], v[30:31], v[44:45]
	v_lshlrev_b32_e32 v45, 16, v40
	v_lshlrev_b32_e32 v65, 16, v41
	v_and_b32_e32 v41, 0xffff0000, v41
	v_and_b32_e32 v40, 0xffff0000, v39
	s_waitcnt vmcnt(4)
	v_lshlrev_b32_e32 v16, 16, v36
	v_lshlrev_b32_e32 v44, 16, v38
	v_and_b32_e32 v62, 0xffff0000, v38
	v_lshlrev_b32_e32 v64, 16, v39
	v_pk_mul_f32 v[38:39], v[30:31], v[40:41]
	v_mul_f32_e32 v41, v31, v16
	v_and_b32_e32 v16, 0xffff0000, v36
	v_mul_f32_e32 v67, v31, v16
	v_lshlrev_b32_e32 v16, 16, v37
	v_mul_f32_e32 v16, v31, v16
	v_mul_f32_e32 v69, v2, v16
	v_and_b32_e32 v16, 0xffff0000, v37
	v_mul_f32_e32 v16, v31, v16
	v_mul_f32_e32 v17, v30, v17
	v_mul_f32_e32 v37, v3, v16
	v_lshlrev_b32_e32 v72, 16, v35
	v_and_b32_e32 v73, 0xffff0000, v35
	v_mov_b32_e32 v16, v31
	v_pk_mul_f32 v[72:73], v[16:17], v[72:73] op_sel_hi:[0,1]
	v_lshlrev_b32_e32 v70, 16, v33
	v_and_b32_e32 v71, 0xffff0000, v33
	v_pk_mul_f32 v[72:73], v[14:15], v[72:73]
	v_and_b32_e32 v33, 0xffff0000, v34
	v_pk_fma_f32 v[70:71], v[30:31], v[70:71], v[72:73] op_sel_hi:[0,1,1]
	v_lshlrev_b32_e32 v72, 16, v32
	v_and_b32_e32 v73, 0xffff0000, v32
	v_lshlrev_b32_e32 v32, 16, v34
	v_pk_mul_f32 v[32:33], v[16:17], v[32:33] op_sel_hi:[0,1]
	v_pk_mul_f32 v[32:33], v[12:13], v[32:33]
	v_mov_b32_e32 v40, v71
	v_pk_fma_f32 v[32:33], v[30:31], v[72:73], v[32:33] op_sel_hi:[0,1,1]
	v_pk_mov_b32 v[72:73], v[70:71], v[0:1] op_sel:[1,0]
	v_pk_mov_b32 v[78:79], v[32:33], v[0:1] op_sel:[1,0]
	v_pk_mul_f32 v[72:73], v[72:73], v[40:41]
	v_mov_b32_e32 v40, v33
	v_mov_b32_e32 v34, v70
	v_mov_b32_e32 v35, v30
	v_mov_b32_e32 v46, v70
	v_mov_b32_e32 v74, v32
	v_mov_b32_e32 v75, v30
	v_mov_b32_e32 v76, v32
	v_mov_b32_e32 v77, v47
	v_pk_mul_f32 v[40:41], v[78:79], v[40:41]
	v_pk_fma_f32 v[34:35], v[34:35], v[46:47], v[72:73]
	v_pk_fma_f32 v[40:41], v[74:75], v[76:77], v[40:41]
	v_pk_mul_f32 v[60:61], v[30:31], v[60:61]
	v_pk_add_f32 v[46:47], v[40:41], v[34:35]
	v_pk_mul_f32 v[34:35], v[40:41], v[34:35]
	v_pk_mul_f32 v[56:57], v[30:31], v[56:57]
	v_pk_mul_f32 v[58:59], v[30:31], v[58:59]
	v_mov_b32_e32 v47, v35
	v_mov_b32_e32 v34, v61
	v_mov_b32_e32 v35, v43
	v_mov_b32_e32 v61, v42
	v_pk_fma_f32 v[34:35], v[10:11], v[34:35], v[60:61]
	v_mov_b32_e32 v60, v57
	v_mov_b32_e32 v61, v59
	v_mov_b32_e32 v57, v58
	v_pk_fma_f32 v[56:57], v[8:9], v[60:61], v[56:57]
	v_mov_b32_e32 v61, v1
	v_mov_b32_e32 v60, v57
	v_mov_b32_e32 v66, v57
	v_mov_b32_e32 v42, v35
	v_mov_b32_e32 v43, v1
	v_mov_b32_e32 v58, v56
	v_mov_b32_e32 v59, v30
	v_mov_b32_e32 v28, v56
	v_pk_mul_f32 v[60:61], v[60:61], v[66:67]
	v_mov_b32_e32 v66, v35
	v_mul_f32_e32 v19, v30, v19
	v_pk_mul_f32 v[44:45], v[30:31], v[44:45]
	v_pk_mul_f32 v[62:63], v[30:31], v[62:63]
	v_pk_mul_f32 v[64:65], v[30:31], v[64:65]
	v_pk_fma_f32 v[58:59], v[58:59], v[28:29], v[60:61]
	v_mov_b32_e32 v60, v34
	v_mov_b32_e32 v61, v30
	v_mov_b32_e32 v28, v34
	v_pk_mul_f32 v[30:31], v[42:43], v[66:67]
	s_ashr_i32 s13, s12, 31
	v_pk_fma_f32 v[28:29], v[60:61], v[28:29], v[30:31]
	s_nop 0
	v_pk_add_f32 v[30:31], v[58:59], v[28:29]
	v_pk_mul_f32 v[28:29], v[58:59], v[28:29]
	v_mov_b32_e32 v58, v41
	v_mov_b32_e32 v31, v29
	v_pk_add_f32 v[28:29], v[46:47], v[30:31]
	v_mov_b32_e32 v30, v65
	v_mov_b32_e32 v31, v39
	v_mov_b32_e32 v65, v38
	v_pk_fma_f32 v[30:31], v[6:7], v[30:31], v[64:65]
	s_nop 0
	v_mov_b32_e32 v36, v30
	v_mov_b32_e32 v16, v30
	v_pk_add_f32 v[16:17], v[36:37], v[16:17]
	v_mul_f32_e32 v18, v31, v31
	v_pk_fma_f32 v[36:37], v[30:31], v[30:31], v[18:19] op_sel_hi:[1,1,0]
	v_pk_mul_f32 v[38:39], v[16:17], v[16:17]
	s_nop 0
	v_mov_b32_e32 v37, v39
	v_mov_b32_e32 v38, v45
	v_mov_b32_e32 v39, v63
	v_mov_b32_e32 v45, v62
	v_pk_fma_f32 v[38:39], v[4:5], v[38:39], v[44:45]
	s_nop 0
	v_mov_b32_e32 v68, v38
	v_mov_b32_e32 v18, v38
	v_pk_add_f32 v[18:19], v[68:69], v[18:19]
	v_mul_f32_e32 v16, v39, v39
	v_pk_fma_f32 v[42:43], v[38:39], v[38:39], v[16:17] op_sel_hi:[1,1,0]
	v_pk_mul_f32 v[44:45], v[18:19], v[18:19]
	s_nop 0
	v_mov_b32_e32 v43, v45
	v_pk_add_f32 v[36:37], v[42:43], v[36:37]
	s_nop 0
	v_pk_add_f32 v[28:29], v[28:29], v[36:37]
	s_nop 0
	v_add_f32_e32 v16, v28, v29
	ds_bpermute_b32 v18, v20, v16
	s_waitcnt lgkmcnt(0)
	v_add_f32_e32 v16, v16, v18
	ds_bpermute_b32 v18, v48, v16
	s_waitcnt lgkmcnt(0)
	v_add_f32_e32 v16, v16, v18
	ds_bpermute_b32 v18, v49, v16
	s_waitcnt lgkmcnt(0)
	v_add_f32_e32 v16, v16, v18
	ds_bpermute_b32 v18, v50, v16
	s_waitcnt lgkmcnt(0)
	v_add_f32_e32 v16, v16, v18
	ds_bpermute_b32 v18, v51, v16
	s_waitcnt lgkmcnt(0)
	v_add_f32_e32 v16, v16, v18
	ds_bpermute_b32 v18, v52, v16
	s_waitcnt lgkmcnt(0)
	v_add_f32_e32 v16, v16, v18
	v_fmamk_f32 v16, v16, 0x3a800000, v53
	v_mul_f32_e32 v18, 0x4f800000, v16
	v_cmp_gt_f32_e32 vcc, s19, v16
	s_nop 1
	v_cndmask_b32_e32 v16, v16, v18, vcc
	v_sqrt_f32_e32 v18, v16
	s_nop 0
	v_add_u32_e32 v28, -1, v18
	v_fma_f32 v29, -v28, v18, v16
	v_cmp_ge_f32_e64 s[0:1], 0, v29
	v_add_u32_e32 v29, 1, v18
	s_nop 0
	v_cndmask_b32_e64 v28, v18, v28, s[0:1]
	v_fma_f32 v18, -v29, v18, v16
	v_cmp_lt_f32_e64 s[0:1], 0, v18
	s_nop 1
	v_cndmask_b32_e64 v18, v28, v29, s[0:1]
	v_mul_f32_e32 v28, 0x37800000, v18
	v_cndmask_b32_e32 v18, v18, v28, vcc
	v_cmp_class_f32_e32 vcc, v16, v54
	s_nop 1
	v_cndmask_b32_e32 v16, v18, v16, vcc
	v_div_scale_f32 v18, s[0:1], v16, v16, 1.0
	v_rcp_f32_e32 v36, v18
	s_lshl_b64 s[0:1], s[12:13], 11
	v_lshl_add_u64 v[28:29], v[22:23], 0, s[0:1]
	v_fma_f32 v37, -v18, v36, 1.0
	v_fmac_f32_e32 v36, v37, v36
	v_div_scale_f32 v37, vcc, 1.0, v16, 1.0
	v_mul_f32_e32 v40, v37, v36
	v_fma_f32 v42, -v18, v40, v37
	v_fmac_f32_e32 v40, v42, v36
	v_fma_f32 v18, -v18, v40, v37
	v_div_fmas_f32 v18, v18, v36, v40
	v_div_fixup_f32 v18, v18, v16, 1.0
	v_pk_mul_f32 v[32:33], v[18:19], v[32:33] op_sel_hi:[0,1]
	v_pk_mul_f32 v[36:37], v[18:19], v[70:71] op_sel_hi:[0,1]
	v_cvt_pk_bf16_f32 v32, v32, v33
	v_cvt_pk_bf16_f32 v33, v36, v37
	global_store_dwordx2 v[28:29], v[32:33], off sc1
	v_pk_mul_f32 v[32:33], v[18:19], v[56:57] op_sel_hi:[0,1]
	v_pk_mul_f32 v[34:35], v[18:19], v[34:35] op_sel_hi:[0,1]
	v_cvt_pk_bf16_f32 v32, v32, v33
	v_cvt_pk_bf16_f32 v33, v34, v35
	global_store_dwordx2 v[28:29], v[32:33], off offset:512 sc1
	v_pk_mul_f32 v[32:33], v[18:19], v[38:39] op_sel_hi:[0,1]
	v_pk_mul_f32 v[30:31], v[18:19], v[30:31] op_sel_hi:[0,1]
	v_mov_b32_e32 v16, v19
	v_cvt_pk_bf16_f32 v32, v32, v33
	v_cvt_pk_bf16_f32 v33, v30, v31
	v_pk_mul_f32 v[30:31], v[18:19], v[58:59] op_sel_hi:[0,1]
	v_pk_mul_f32 v[16:17], v[18:19], v[16:17] op_sel_hi:[0,1]
	v_cvt_pk_bf16_f32 v30, v30, v31
	v_cvt_pk_bf16_f32 v31, v16, v17
	global_store_dwordx2 v[28:29], v[32:33], off offset:1024 sc1
	global_store_dwordx2 v[28:29], v[30:31], off offset:1536 sc1
	s_branch .LBB0_806
